# P0 mod GEMV: k loop fully unrolled with the w_ada loads kept 48 deep in a 64-register ring (was 16 loads per round trip)
# speedup vs baseline: 1.0098x; 1.0098x over previous
.LBB0_24:
	s_add_u32 s24, s6, s10
	s_addc_u32 s25, s7, s11
	global_load_dword v100, v68, s[24:25]
	s_add_u32 s24, s24, 0x6000
	s_addc_u32 s25, s25, 0
	global_load_dword v101, v68, s[24:25]
	s_add_u32 s24, s24, 0x6000
	s_addc_u32 s25, s25, 0
	global_load_dword v102, v68, s[24:25]
	s_add_u32 s24, s24, 0x6000
	s_addc_u32 s25, s25, 0
	global_load_dword v103, v68, s[24:25]
	s_add_u32 s24, s24, 0x6000
	s_addc_u32 s25, s25, 0
	global_load_dword v104, v68, s[24:25]
	s_add_u32 s24, s24, 0x6000
	s_addc_u32 s25, s25, 0
	global_load_dword v105, v68, s[24:25]
	s_add_u32 s24, s24, 0x6000
	s_addc_u32 s25, s25, 0
	global_load_dword v106, v68, s[24:25]
	s_add_u32 s24, s24, 0x6000
	s_addc_u32 s25, s25, 0
	global_load_dword v107, v68, s[24:25]
	s_add_u32 s24, s24, 0x6000
	s_addc_u32 s25, s25, 0
	global_load_dword v108, v68, s[24:25]
	s_add_u32 s24, s24, 0x6000
	s_addc_u32 s25, s25, 0
	global_load_dword v109, v68, s[24:25]
	s_add_u32 s24, s24, 0x6000
	s_addc_u32 s25, s25, 0
	global_load_dword v110, v68, s[24:25]
	s_add_u32 s24, s24, 0x6000
	s_addc_u32 s25, s25, 0
	global_load_dword v111, v68, s[24:25]
	s_add_u32 s24, s24, 0x6000
	s_addc_u32 s25, s25, 0
	global_load_dword v112, v68, s[24:25]
	s_add_u32 s24, s24, 0x6000
	s_addc_u32 s25, s25, 0
	global_load_dword v113, v68, s[24:25]
	s_add_u32 s24, s24, 0x6000
	s_addc_u32 s25, s25, 0
	global_load_dword v114, v68, s[24:25]
	s_add_u32 s24, s24, 0x6000
	s_addc_u32 s25, s25, 0
	global_load_dword v115, v68, s[24:25]
	s_add_u32 s24, s24, 0x6000
	s_addc_u32 s25, s25, 0
	global_load_dword v116, v68, s[24:25]
	s_add_u32 s24, s24, 0x6000
	s_addc_u32 s25, s25, 0
	global_load_dword v117, v68, s[24:25]
	s_add_u32 s24, s24, 0x6000
	s_addc_u32 s25, s25, 0
	global_load_dword v118, v68, s[24:25]
	s_add_u32 s24, s24, 0x6000
	s_addc_u32 s25, s25, 0
	global_load_dword v119, v68, s[24:25]
	s_add_u32 s24, s24, 0x6000
	s_addc_u32 s25, s25, 0
	global_load_dword v120, v68, s[24:25]
	s_add_u32 s24, s24, 0x6000
	s_addc_u32 s25, s25, 0
	global_load_dword v121, v68, s[24:25]
	s_add_u32 s24, s24, 0x6000
	s_addc_u32 s25, s25, 0
	global_load_dword v122, v68, s[24:25]
	s_add_u32 s24, s24, 0x6000
	s_addc_u32 s25, s25, 0
	global_load_dword v123, v68, s[24:25]
	s_add_u32 s24, s24, 0x6000
	s_addc_u32 s25, s25, 0
	global_load_dword v124, v68, s[24:25]
	s_add_u32 s24, s24, 0x6000
	s_addc_u32 s25, s25, 0
	global_load_dword v125, v68, s[24:25]
	s_add_u32 s24, s24, 0x6000
	s_addc_u32 s25, s25, 0
	global_load_dword v126, v68, s[24:25]
	s_add_u32 s24, s24, 0x6000
	s_addc_u32 s25, s25, 0
	global_load_dword v127, v68, s[24:25]
	s_add_u32 s24, s24, 0x6000
	s_addc_u32 s25, s25, 0
	global_load_dword v128, v68, s[24:25]
	s_add_u32 s24, s24, 0x6000
	s_addc_u32 s25, s25, 0
	global_load_dword v129, v68, s[24:25]
	s_add_u32 s24, s24, 0x6000
	s_addc_u32 s25, s25, 0
	global_load_dword v130, v68, s[24:25]
	s_add_u32 s24, s24, 0x6000
	s_addc_u32 s25, s25, 0
	global_load_dword v131, v68, s[24:25]
	s_add_u32 s24, s24, 0x6000
	s_addc_u32 s25, s25, 0
	global_load_dword v132, v68, s[24:25]
	s_add_u32 s24, s24, 0x6000
	s_addc_u32 s25, s25, 0
	global_load_dword v133, v68, s[24:25]
	s_add_u32 s24, s24, 0x6000
	s_addc_u32 s25, s25, 0
	global_load_dword v134, v68, s[24:25]
	s_add_u32 s24, s24, 0x6000
	s_addc_u32 s25, s25, 0
	global_load_dword v135, v68, s[24:25]
	s_add_u32 s24, s24, 0x6000
	s_addc_u32 s25, s25, 0
	global_load_dword v136, v68, s[24:25]
	s_add_u32 s24, s24, 0x6000
	s_addc_u32 s25, s25, 0
	global_load_dword v137, v68, s[24:25]
	s_add_u32 s24, s24, 0x6000
	s_addc_u32 s25, s25, 0
	global_load_dword v138, v68, s[24:25]
	s_add_u32 s24, s24, 0x6000
	s_addc_u32 s25, s25, 0
	global_load_dword v139, v68, s[24:25]
	s_add_u32 s24, s24, 0x6000
	s_addc_u32 s25, s25, 0
	global_load_dword v140, v68, s[24:25]
	s_add_u32 s24, s24, 0x6000
	s_addc_u32 s25, s25, 0
	global_load_dword v141, v68, s[24:25]
	s_add_u32 s24, s24, 0x6000
	s_addc_u32 s25, s25, 0
	global_load_dword v142, v68, s[24:25]
	s_add_u32 s24, s24, 0x6000
	s_addc_u32 s25, s25, 0
	global_load_dword v143, v68, s[24:25]
	s_add_u32 s24, s24, 0x6000
	s_addc_u32 s25, s25, 0
	global_load_dword v146, v68, s[24:25]
	s_add_u32 s24, s24, 0x6000
	s_addc_u32 s25, s25, 0
	global_load_dword v147, v68, s[24:25]
	s_add_u32 s24, s24, 0x6000
	s_addc_u32 s25, s25, 0
	global_load_dword v148, v68, s[24:25]
	s_add_u32 s24, s24, 0x6000
	s_addc_u32 s25, s25, 0
	global_load_dword v149, v68, s[24:25]
	s_add_u32 s24, s24, 0x6000
	s_addc_u32 s25, s25, 0
	global_load_dword v150, v68, s[24:25]
	s_add_u32 s24, s24, 0x6000
	s_addc_u32 s25, s25, 0
	global_load_dword v151, v68, s[24:25]
	s_add_u32 s24, s24, 0x6000
	s_addc_u32 s25, s25, 0
	global_load_dword v152, v68, s[24:25]
	s_add_u32 s24, s24, 0x6000
	s_addc_u32 s25, s25, 0
	global_load_dword v153, v68, s[24:25]
	s_add_u32 s24, s24, 0x6000
	s_addc_u32 s25, s25, 0
	global_load_dword v154, v68, s[24:25]
	s_add_u32 s24, s24, 0x6000
	s_addc_u32 s25, s25, 0
	global_load_dword v155, v68, s[24:25]
	s_add_u32 s24, s24, 0x6000
	s_addc_u32 s25, s25, 0
	global_load_dword v156, v68, s[24:25]
	s_add_u32 s24, s24, 0x6000
	s_addc_u32 s25, s25, 0
	global_load_dword v157, v68, s[24:25]
	s_add_u32 s24, s24, 0x6000
	s_addc_u32 s25, s25, 0
	global_load_dword v158, v68, s[24:25]
	s_add_u32 s24, s24, 0x6000
	s_addc_u32 s25, s25, 0
	global_load_dword v159, v68, s[24:25]
	s_add_u32 s24, s24, 0x6000
	s_addc_u32 s25, s25, 0
	global_load_dword v160, v68, s[24:25]
	s_add_u32 s24, s24, 0x6000
	s_addc_u32 s25, s25, 0
	global_load_dword v161, v68, s[24:25]
	s_add_u32 s24, s24, 0x6000
	s_addc_u32 s25, s25, 0
	global_load_dword v162, v68, s[24:25]
	s_add_u32 s24, s24, 0x6000
	s_addc_u32 s25, s25, 0
	global_load_dword v163, v68, s[24:25]
	s_add_u32 s24, s24, 0x6000
	s_addc_u32 s25, s25, 0
	global_load_dword v164, v68, s[24:25]
	s_add_u32 s24, s24, 0x6000
	s_addc_u32 s25, s25, 0
	global_load_dword v165, v68, s[24:25]
	s_add_u32 s24, s24, 0x6000
	s_addc_u32 s25, s25, 0
	v_mov_b32_e32 v5, s12
	ds_read_b128 v[50:53], v5
	ds_read_b128 v[22:25], v5 offset:4096
	ds_read_b128 v[26:29], v5 offset:8192
	ds_read_b128 v[30:33], v5 offset:12288
	ds_read_b128 v[34:37], v5 offset:16384
	ds_read_b128 v[38:41], v5 offset:20480
	ds_read_b128 v[42:45], v5 offset:24576
	ds_read_b128 v[46:49], v5 offset:28672
	ds_read_b128 v[54:57], v5 offset:32768
	s_waitcnt vmcnt(60) lgkmcnt(0)
	v_fmac_f32_e32 v8, v100, v50
	v_fmac_f32_e32 v9, v100, v22
	v_fmac_f32_e32 v10, v100, v26
	v_fmac_f32_e32 v11, v100, v30
	v_fmac_f32_e32 v12, v100, v34
	v_fmac_f32_e32 v13, v100, v38
	v_fmac_f32_e32 v14, v100, v42
	v_fmac_f32_e32 v15, v100, v46
	v_fmac_f32_e32 v0, v100, v54
	v_fmac_f32_e32 v8, v101, v51
	v_fmac_f32_e32 v9, v101, v23
	v_fmac_f32_e32 v10, v101, v27
	v_fmac_f32_e32 v11, v101, v31
	v_fmac_f32_e32 v12, v101, v35
	v_fmac_f32_e32 v13, v101, v39
	v_fmac_f32_e32 v14, v101, v43
	v_fmac_f32_e32 v15, v101, v47
	v_fmac_f32_e32 v0, v101, v55
	v_fmac_f32_e32 v8, v102, v52
	v_fmac_f32_e32 v9, v102, v24
	v_fmac_f32_e32 v10, v102, v28
	v_fmac_f32_e32 v11, v102, v32
	v_fmac_f32_e32 v12, v102, v36
	v_fmac_f32_e32 v13, v102, v40
	v_fmac_f32_e32 v14, v102, v44
	v_fmac_f32_e32 v15, v102, v48
	v_fmac_f32_e32 v0, v102, v56
	v_fmac_f32_e32 v8, v103, v53
	v_fmac_f32_e32 v9, v103, v25
	v_fmac_f32_e32 v10, v103, v29
	v_fmac_f32_e32 v11, v103, v33
	v_fmac_f32_e32 v12, v103, v37
	v_fmac_f32_e32 v13, v103, v41
	v_fmac_f32_e32 v14, v103, v45
	v_fmac_f32_e32 v15, v103, v49
	v_fmac_f32_e32 v0, v103, v57
	ds_read_b128 v[50:53], v5 offset:16
	ds_read_b128 v[22:25], v5 offset:4112
	ds_read_b128 v[26:29], v5 offset:8208
	ds_read_b128 v[30:33], v5 offset:12304
	ds_read_b128 v[34:37], v5 offset:16400
	ds_read_b128 v[38:41], v5 offset:20496
	ds_read_b128 v[42:45], v5 offset:24592
	ds_read_b128 v[46:49], v5 offset:28688
	ds_read_b128 v[54:57], v5 offset:32784
	s_waitcnt vmcnt(56) lgkmcnt(0)
	v_fmac_f32_e32 v8, v104, v50
	v_fmac_f32_e32 v9, v104, v22
	v_fmac_f32_e32 v10, v104, v26
	v_fmac_f32_e32 v11, v104, v30
	v_fmac_f32_e32 v12, v104, v34
	v_fmac_f32_e32 v13, v104, v38
	v_fmac_f32_e32 v14, v104, v42
	v_fmac_f32_e32 v15, v104, v46
	v_fmac_f32_e32 v0, v104, v54
	v_fmac_f32_e32 v8, v105, v51
	v_fmac_f32_e32 v9, v105, v23
	v_fmac_f32_e32 v10, v105, v27
	v_fmac_f32_e32 v11, v105, v31
	v_fmac_f32_e32 v12, v105, v35
	v_fmac_f32_e32 v13, v105, v39
	v_fmac_f32_e32 v14, v105, v43
	v_fmac_f32_e32 v15, v105, v47
	v_fmac_f32_e32 v0, v105, v55
	v_fmac_f32_e32 v8, v106, v52
	v_fmac_f32_e32 v9, v106, v24
	v_fmac_f32_e32 v10, v106, v28
	v_fmac_f32_e32 v11, v106, v32
	v_fmac_f32_e32 v12, v106, v36
	v_fmac_f32_e32 v13, v106, v40
	v_fmac_f32_e32 v14, v106, v44
	v_fmac_f32_e32 v15, v106, v48
	v_fmac_f32_e32 v0, v106, v56
	v_fmac_f32_e32 v8, v107, v53
	v_fmac_f32_e32 v9, v107, v25
	v_fmac_f32_e32 v10, v107, v29
	v_fmac_f32_e32 v11, v107, v33
	v_fmac_f32_e32 v12, v107, v37
	v_fmac_f32_e32 v13, v107, v41
	v_fmac_f32_e32 v14, v107, v45
	v_fmac_f32_e32 v15, v107, v49
	v_fmac_f32_e32 v0, v107, v57
	ds_read_b128 v[50:53], v5 offset:32
	ds_read_b128 v[22:25], v5 offset:4128
	ds_read_b128 v[26:29], v5 offset:8224
	ds_read_b128 v[30:33], v5 offset:12320
	ds_read_b128 v[34:37], v5 offset:16416
	ds_read_b128 v[38:41], v5 offset:20512
	ds_read_b128 v[42:45], v5 offset:24608
	ds_read_b128 v[46:49], v5 offset:28704
	ds_read_b128 v[54:57], v5 offset:32800
	s_waitcnt vmcnt(52) lgkmcnt(0)
	v_fmac_f32_e32 v8, v108, v50
	v_fmac_f32_e32 v9, v108, v22
	v_fmac_f32_e32 v10, v108, v26
	v_fmac_f32_e32 v11, v108, v30
	v_fmac_f32_e32 v12, v108, v34
	v_fmac_f32_e32 v13, v108, v38
	v_fmac_f32_e32 v14, v108, v42
	v_fmac_f32_e32 v15, v108, v46
	v_fmac_f32_e32 v0, v108, v54
	v_fmac_f32_e32 v8, v109, v51
	v_fmac_f32_e32 v9, v109, v23
	v_fmac_f32_e32 v10, v109, v27
	v_fmac_f32_e32 v11, v109, v31
	v_fmac_f32_e32 v12, v109, v35
	v_fmac_f32_e32 v13, v109, v39
	v_fmac_f32_e32 v14, v109, v43
	v_fmac_f32_e32 v15, v109, v47
	v_fmac_f32_e32 v0, v109, v55
	v_fmac_f32_e32 v8, v110, v52
	v_fmac_f32_e32 v9, v110, v24
	v_fmac_f32_e32 v10, v110, v28
	v_fmac_f32_e32 v11, v110, v32
	v_fmac_f32_e32 v12, v110, v36
	v_fmac_f32_e32 v13, v110, v40
	v_fmac_f32_e32 v14, v110, v44
	v_fmac_f32_e32 v15, v110, v48
	v_fmac_f32_e32 v0, v110, v56
	v_fmac_f32_e32 v8, v111, v53
	v_fmac_f32_e32 v9, v111, v25
	v_fmac_f32_e32 v10, v111, v29
	v_fmac_f32_e32 v11, v111, v33
	v_fmac_f32_e32 v12, v111, v37
	v_fmac_f32_e32 v13, v111, v41
	v_fmac_f32_e32 v14, v111, v45
	v_fmac_f32_e32 v15, v111, v49
	v_fmac_f32_e32 v0, v111, v57
	ds_read_b128 v[50:53], v5 offset:48
	ds_read_b128 v[22:25], v5 offset:4144
	ds_read_b128 v[26:29], v5 offset:8240
	ds_read_b128 v[30:33], v5 offset:12336
	ds_read_b128 v[34:37], v5 offset:16432
	ds_read_b128 v[38:41], v5 offset:20528
	ds_read_b128 v[42:45], v5 offset:24624
	ds_read_b128 v[46:49], v5 offset:28720
	ds_read_b128 v[54:57], v5 offset:32816
	s_waitcnt vmcnt(48) lgkmcnt(0)
	v_fmac_f32_e32 v8, v112, v50
	v_fmac_f32_e32 v9, v112, v22
	v_fmac_f32_e32 v10, v112, v26
	v_fmac_f32_e32 v11, v112, v30
	v_fmac_f32_e32 v12, v112, v34
	v_fmac_f32_e32 v13, v112, v38
	v_fmac_f32_e32 v14, v112, v42
	v_fmac_f32_e32 v15, v112, v46
	v_fmac_f32_e32 v0, v112, v54
	v_fmac_f32_e32 v8, v113, v51
	v_fmac_f32_e32 v9, v113, v23
	v_fmac_f32_e32 v10, v113, v27
	v_fmac_f32_e32 v11, v113, v31
	v_fmac_f32_e32 v12, v113, v35
	v_fmac_f32_e32 v13, v113, v39
	v_fmac_f32_e32 v14, v113, v43
	v_fmac_f32_e32 v15, v113, v47
	v_fmac_f32_e32 v0, v113, v55
	v_fmac_f32_e32 v8, v114, v52
	v_fmac_f32_e32 v9, v114, v24
	v_fmac_f32_e32 v10, v114, v28
	v_fmac_f32_e32 v11, v114, v32
	v_fmac_f32_e32 v12, v114, v36
	v_fmac_f32_e32 v13, v114, v40
	v_fmac_f32_e32 v14, v114, v44
	v_fmac_f32_e32 v15, v114, v48
	v_fmac_f32_e32 v0, v114, v56
	v_fmac_f32_e32 v8, v115, v53
	v_fmac_f32_e32 v9, v115, v25
	v_fmac_f32_e32 v10, v115, v29
	v_fmac_f32_e32 v11, v115, v33
	v_fmac_f32_e32 v12, v115, v37
	v_fmac_f32_e32 v13, v115, v41
	v_fmac_f32_e32 v14, v115, v45
	v_fmac_f32_e32 v15, v115, v49
	v_fmac_f32_e32 v0, v115, v57
	s_add_i32 s12, s12, 64
	global_load_dword v100, v68, s[24:25]
	s_add_u32 s24, s24, 0x6000
	s_addc_u32 s25, s25, 0
	global_load_dword v101, v68, s[24:25]
	s_add_u32 s24, s24, 0x6000
	s_addc_u32 s25, s25, 0
	global_load_dword v102, v68, s[24:25]
	s_add_u32 s24, s24, 0x6000
	s_addc_u32 s25, s25, 0
	global_load_dword v103, v68, s[24:25]
	s_add_u32 s24, s24, 0x6000
	s_addc_u32 s25, s25, 0
	global_load_dword v104, v68, s[24:25]
	s_add_u32 s24, s24, 0x6000
	s_addc_u32 s25, s25, 0
	global_load_dword v105, v68, s[24:25]
	s_add_u32 s24, s24, 0x6000
	s_addc_u32 s25, s25, 0
	global_load_dword v106, v68, s[24:25]
	s_add_u32 s24, s24, 0x6000
	s_addc_u32 s25, s25, 0
	global_load_dword v107, v68, s[24:25]
	s_add_u32 s24, s24, 0x6000
	s_addc_u32 s25, s25, 0
	global_load_dword v108, v68, s[24:25]
	s_add_u32 s24, s24, 0x6000
	s_addc_u32 s25, s25, 0
	global_load_dword v109, v68, s[24:25]
	s_add_u32 s24, s24, 0x6000
	s_addc_u32 s25, s25, 0
	global_load_dword v110, v68, s[24:25]
	s_add_u32 s24, s24, 0x6000
	s_addc_u32 s25, s25, 0
	global_load_dword v111, v68, s[24:25]
	s_add_u32 s24, s24, 0x6000
	s_addc_u32 s25, s25, 0
	global_load_dword v112, v68, s[24:25]
	s_add_u32 s24, s24, 0x6000
	s_addc_u32 s25, s25, 0
	global_load_dword v113, v68, s[24:25]
	s_add_u32 s24, s24, 0x6000
	s_addc_u32 s25, s25, 0
	global_load_dword v114, v68, s[24:25]
	s_add_u32 s24, s24, 0x6000
	s_addc_u32 s25, s25, 0
	global_load_dword v115, v68, s[24:25]
	s_add_u32 s24, s24, 0x6000
	s_addc_u32 s25, s25, 0
	v_mov_b32_e32 v5, s12
	ds_read_b128 v[50:53], v5
	ds_read_b128 v[22:25], v5 offset:4096
	ds_read_b128 v[26:29], v5 offset:8192
	ds_read_b128 v[30:33], v5 offset:12288
	ds_read_b128 v[34:37], v5 offset:16384
	ds_read_b128 v[38:41], v5 offset:20480
	ds_read_b128 v[42:45], v5 offset:24576
	ds_read_b128 v[46:49], v5 offset:28672
	ds_read_b128 v[54:57], v5 offset:32768
	s_waitcnt vmcnt(60) lgkmcnt(0)
	v_fmac_f32_e32 v8, v116, v50
	v_fmac_f32_e32 v9, v116, v22
	v_fmac_f32_e32 v10, v116, v26
	v_fmac_f32_e32 v11, v116, v30
	v_fmac_f32_e32 v12, v116, v34
	v_fmac_f32_e32 v13, v116, v38
	v_fmac_f32_e32 v14, v116, v42
	v_fmac_f32_e32 v15, v116, v46
	v_fmac_f32_e32 v0, v116, v54
	v_fmac_f32_e32 v8, v117, v51
	v_fmac_f32_e32 v9, v117, v23
	v_fmac_f32_e32 v10, v117, v27
	v_fmac_f32_e32 v11, v117, v31
	v_fmac_f32_e32 v12, v117, v35
	v_fmac_f32_e32 v13, v117, v39
	v_fmac_f32_e32 v14, v117, v43
	v_fmac_f32_e32 v15, v117, v47
	v_fmac_f32_e32 v0, v117, v55
	v_fmac_f32_e32 v8, v118, v52
	v_fmac_f32_e32 v9, v118, v24
	v_fmac_f32_e32 v10, v118, v28
	v_fmac_f32_e32 v11, v118, v32
	v_fmac_f32_e32 v12, v118, v36
	v_fmac_f32_e32 v13, v118, v40
	v_fmac_f32_e32 v14, v118, v44
	v_fmac_f32_e32 v15, v118, v48
	v_fmac_f32_e32 v0, v118, v56
	v_fmac_f32_e32 v8, v119, v53
	v_fmac_f32_e32 v9, v119, v25
	v_fmac_f32_e32 v10, v119, v29
	v_fmac_f32_e32 v11, v119, v33
	v_fmac_f32_e32 v12, v119, v37
	v_fmac_f32_e32 v13, v119, v41
	v_fmac_f32_e32 v14, v119, v45
	v_fmac_f32_e32 v15, v119, v49
	v_fmac_f32_e32 v0, v119, v57
	ds_read_b128 v[50:53], v5 offset:16
	ds_read_b128 v[22:25], v5 offset:4112
	ds_read_b128 v[26:29], v5 offset:8208
	ds_read_b128 v[30:33], v5 offset:12304
	ds_read_b128 v[34:37], v5 offset:16400
	ds_read_b128 v[38:41], v5 offset:20496
	ds_read_b128 v[42:45], v5 offset:24592
	ds_read_b128 v[46:49], v5 offset:28688
	ds_read_b128 v[54:57], v5 offset:32784
	s_waitcnt vmcnt(56) lgkmcnt(0)
	v_fmac_f32_e32 v8, v120, v50
	v_fmac_f32_e32 v9, v120, v22
	v_fmac_f32_e32 v10, v120, v26
	v_fmac_f32_e32 v11, v120, v30
	v_fmac_f32_e32 v12, v120, v34
	v_fmac_f32_e32 v13, v120, v38
	v_fmac_f32_e32 v14, v120, v42
	v_fmac_f32_e32 v15, v120, v46
	v_fmac_f32_e32 v0, v120, v54
	v_fmac_f32_e32 v8, v121, v51
	v_fmac_f32_e32 v9, v121, v23
	v_fmac_f32_e32 v10, v121, v27
	v_fmac_f32_e32 v11, v121, v31
	v_fmac_f32_e32 v12, v121, v35
	v_fmac_f32_e32 v13, v121, v39
	v_fmac_f32_e32 v14, v121, v43
	v_fmac_f32_e32 v15, v121, v47
	v_fmac_f32_e32 v0, v121, v55
	v_fmac_f32_e32 v8, v122, v52
	v_fmac_f32_e32 v9, v122, v24
	v_fmac_f32_e32 v10, v122, v28
	v_fmac_f32_e32 v11, v122, v32
	v_fmac_f32_e32 v12, v122, v36
	v_fmac_f32_e32 v13, v122, v40
	v_fmac_f32_e32 v14, v122, v44
	v_fmac_f32_e32 v15, v122, v48
	v_fmac_f32_e32 v0, v122, v56
	v_fmac_f32_e32 v8, v123, v53
	v_fmac_f32_e32 v9, v123, v25
	v_fmac_f32_e32 v10, v123, v29
	v_fmac_f32_e32 v11, v123, v33
	v_fmac_f32_e32 v12, v123, v37
	v_fmac_f32_e32 v13, v123, v41
	v_fmac_f32_e32 v14, v123, v45
	v_fmac_f32_e32 v15, v123, v49
	v_fmac_f32_e32 v0, v123, v57
	ds_read_b128 v[50:53], v5 offset:32
	ds_read_b128 v[22:25], v5 offset:4128
	ds_read_b128 v[26:29], v5 offset:8224
	ds_read_b128 v[30:33], v5 offset:12320
	ds_read_b128 v[34:37], v5 offset:16416
	ds_read_b128 v[38:41], v5 offset:20512
	ds_read_b128 v[42:45], v5 offset:24608
	ds_read_b128 v[46:49], v5 offset:28704
	ds_read_b128 v[54:57], v5 offset:32800
	s_waitcnt vmcnt(52) lgkmcnt(0)
	v_fmac_f32_e32 v8, v124, v50
	v_fmac_f32_e32 v9, v124, v22
	v_fmac_f32_e32 v10, v124, v26
	v_fmac_f32_e32 v11, v124, v30
	v_fmac_f32_e32 v12, v124, v34
	v_fmac_f32_e32 v13, v124, v38
	v_fmac_f32_e32 v14, v124, v42
	v_fmac_f32_e32 v15, v124, v46
	v_fmac_f32_e32 v0, v124, v54
	v_fmac_f32_e32 v8, v125, v51
	v_fmac_f32_e32 v9, v125, v23
	v_fmac_f32_e32 v10, v125, v27
	v_fmac_f32_e32 v11, v125, v31
	v_fmac_f32_e32 v12, v125, v35
	v_fmac_f32_e32 v13, v125, v39
	v_fmac_f32_e32 v14, v125, v43
	v_fmac_f32_e32 v15, v125, v47
	v_fmac_f32_e32 v0, v125, v55
	v_fmac_f32_e32 v8, v126, v52
	v_fmac_f32_e32 v9, v126, v24
	v_fmac_f32_e32 v10, v126, v28
	v_fmac_f32_e32 v11, v126, v32
	v_fmac_f32_e32 v12, v126, v36
	v_fmac_f32_e32 v13, v126, v40
	v_fmac_f32_e32 v14, v126, v44
	v_fmac_f32_e32 v15, v126, v48
	v_fmac_f32_e32 v0, v126, v56
	v_fmac_f32_e32 v8, v127, v53
	v_fmac_f32_e32 v9, v127, v25
	v_fmac_f32_e32 v10, v127, v29
	v_fmac_f32_e32 v11, v127, v33
	v_fmac_f32_e32 v12, v127, v37
	v_fmac_f32_e32 v13, v127, v41
	v_fmac_f32_e32 v14, v127, v45
	v_fmac_f32_e32 v15, v127, v49
	v_fmac_f32_e32 v0, v127, v57
	ds_read_b128 v[50:53], v5 offset:48
	ds_read_b128 v[22:25], v5 offset:4144
	ds_read_b128 v[26:29], v5 offset:8240
	ds_read_b128 v[30:33], v5 offset:12336
	ds_read_b128 v[34:37], v5 offset:16432
	ds_read_b128 v[38:41], v5 offset:20528
	ds_read_b128 v[42:45], v5 offset:24624
	ds_read_b128 v[46:49], v5 offset:28720
	ds_read_b128 v[54:57], v5 offset:32816
	s_waitcnt vmcnt(48) lgkmcnt(0)
	v_fmac_f32_e32 v8, v128, v50
	v_fmac_f32_e32 v9, v128, v22
	v_fmac_f32_e32 v10, v128, v26
	v_fmac_f32_e32 v11, v128, v30
	v_fmac_f32_e32 v12, v128, v34
	v_fmac_f32_e32 v13, v128, v38
	v_fmac_f32_e32 v14, v128, v42
	v_fmac_f32_e32 v15, v128, v46
	v_fmac_f32_e32 v0, v128, v54
	v_fmac_f32_e32 v8, v129, v51
	v_fmac_f32_e32 v9, v129, v23
	v_fmac_f32_e32 v10, v129, v27
	v_fmac_f32_e32 v11, v129, v31
	v_fmac_f32_e32 v12, v129, v35
	v_fmac_f32_e32 v13, v129, v39
	v_fmac_f32_e32 v14, v129, v43
	v_fmac_f32_e32 v15, v129, v47
	v_fmac_f32_e32 v0, v129, v55
	v_fmac_f32_e32 v8, v130, v52
	v_fmac_f32_e32 v9, v130, v24
	v_fmac_f32_e32 v10, v130, v28
	v_fmac_f32_e32 v11, v130, v32
	v_fmac_f32_e32 v12, v130, v36
	v_fmac_f32_e32 v13, v130, v40
	v_fmac_f32_e32 v14, v130, v44
	v_fmac_f32_e32 v15, v130, v48
	v_fmac_f32_e32 v0, v130, v56
	v_fmac_f32_e32 v8, v131, v53
	v_fmac_f32_e32 v9, v131, v25
	v_fmac_f32_e32 v10, v131, v29
	v_fmac_f32_e32 v11, v131, v33
	v_fmac_f32_e32 v12, v131, v37
	v_fmac_f32_e32 v13, v131, v41
	v_fmac_f32_e32 v14, v131, v45
	v_fmac_f32_e32 v15, v131, v49
	v_fmac_f32_e32 v0, v131, v57
	s_add_i32 s12, s12, 64
	global_load_dword v116, v68, s[24:25]
	s_add_u32 s24, s24, 0x6000
	s_addc_u32 s25, s25, 0
	global_load_dword v117, v68, s[24:25]
	s_add_u32 s24, s24, 0x6000
	s_addc_u32 s25, s25, 0
	global_load_dword v118, v68, s[24:25]
	s_add_u32 s24, s24, 0x6000
	s_addc_u32 s25, s25, 0
	global_load_dword v119, v68, s[24:25]
	s_add_u32 s24, s24, 0x6000
	s_addc_u32 s25, s25, 0
	global_load_dword v120, v68, s[24:25]
	s_add_u32 s24, s24, 0x6000
	s_addc_u32 s25, s25, 0
	global_load_dword v121, v68, s[24:25]
	s_add_u32 s24, s24, 0x6000
	s_addc_u32 s25, s25, 0
	global_load_dword v122, v68, s[24:25]
	s_add_u32 s24, s24, 0x6000
	s_addc_u32 s25, s25, 0
	global_load_dword v123, v68, s[24:25]
	s_add_u32 s24, s24, 0x6000
	s_addc_u32 s25, s25, 0
	global_load_dword v124, v68, s[24:25]
	s_add_u32 s24, s24, 0x6000
	s_addc_u32 s25, s25, 0
	global_load_dword v125, v68, s[24:25]
	s_add_u32 s24, s24, 0x6000
	s_addc_u32 s25, s25, 0
	global_load_dword v126, v68, s[24:25]
	s_add_u32 s24, s24, 0x6000
	s_addc_u32 s25, s25, 0
	global_load_dword v127, v68, s[24:25]
	s_add_u32 s24, s24, 0x6000
	s_addc_u32 s25, s25, 0
	global_load_dword v128, v68, s[24:25]
	s_add_u32 s24, s24, 0x6000
	s_addc_u32 s25, s25, 0
	global_load_dword v129, v68, s[24:25]
	s_add_u32 s24, s24, 0x6000
	s_addc_u32 s25, s25, 0
	global_load_dword v130, v68, s[24:25]
	s_add_u32 s24, s24, 0x6000
	s_addc_u32 s25, s25, 0
	global_load_dword v131, v68, s[24:25]
	s_add_u32 s24, s24, 0x6000
	s_addc_u32 s25, s25, 0
	v_mov_b32_e32 v5, s12
	ds_read_b128 v[50:53], v5
	ds_read_b128 v[22:25], v5 offset:4096
	ds_read_b128 v[26:29], v5 offset:8192
	ds_read_b128 v[30:33], v5 offset:12288
	ds_read_b128 v[34:37], v5 offset:16384
	ds_read_b128 v[38:41], v5 offset:20480
	ds_read_b128 v[42:45], v5 offset:24576
	ds_read_b128 v[46:49], v5 offset:28672
	ds_read_b128 v[54:57], v5 offset:32768
	s_waitcnt vmcnt(60) lgkmcnt(0)
	v_fmac_f32_e32 v8, v132, v50
	v_fmac_f32_e32 v9, v132, v22
	v_fmac_f32_e32 v10, v132, v26
	v_fmac_f32_e32 v11, v132, v30
	v_fmac_f32_e32 v12, v132, v34
	v_fmac_f32_e32 v13, v132, v38
	v_fmac_f32_e32 v14, v132, v42
	v_fmac_f32_e32 v15, v132, v46
	v_fmac_f32_e32 v0, v132, v54
	v_fmac_f32_e32 v8, v133, v51
	v_fmac_f32_e32 v9, v133, v23
	v_fmac_f32_e32 v10, v133, v27
	v_fmac_f32_e32 v11, v133, v31
	v_fmac_f32_e32 v12, v133, v35
	v_fmac_f32_e32 v13, v133, v39
	v_fmac_f32_e32 v14, v133, v43
	v_fmac_f32_e32 v15, v133, v47
	v_fmac_f32_e32 v0, v133, v55
	v_fmac_f32_e32 v8, v134, v52
	v_fmac_f32_e32 v9, v134, v24
	v_fmac_f32_e32 v10, v134, v28
	v_fmac_f32_e32 v11, v134, v32
	v_fmac_f32_e32 v12, v134, v36
	v_fmac_f32_e32 v13, v134, v40
	v_fmac_f32_e32 v14, v134, v44
	v_fmac_f32_e32 v15, v134, v48
	v_fmac_f32_e32 v0, v134, v56
	v_fmac_f32_e32 v8, v135, v53
	v_fmac_f32_e32 v9, v135, v25
	v_fmac_f32_e32 v10, v135, v29
	v_fmac_f32_e32 v11, v135, v33
	v_fmac_f32_e32 v12, v135, v37
	v_fmac_f32_e32 v13, v135, v41
	v_fmac_f32_e32 v14, v135, v45
	v_fmac_f32_e32 v15, v135, v49
	v_fmac_f32_e32 v0, v135, v57
	ds_read_b128 v[50:53], v5 offset:16
	ds_read_b128 v[22:25], v5 offset:4112
	ds_read_b128 v[26:29], v5 offset:8208
	ds_read_b128 v[30:33], v5 offset:12304
	ds_read_b128 v[34:37], v5 offset:16400
	ds_read_b128 v[38:41], v5 offset:20496
	ds_read_b128 v[42:45], v5 offset:24592
	ds_read_b128 v[46:49], v5 offset:28688
	ds_read_b128 v[54:57], v5 offset:32784
	s_waitcnt vmcnt(56) lgkmcnt(0)
	v_fmac_f32_e32 v8, v136, v50
	v_fmac_f32_e32 v9, v136, v22
	v_fmac_f32_e32 v10, v136, v26
	v_fmac_f32_e32 v11, v136, v30
	v_fmac_f32_e32 v12, v136, v34
	v_fmac_f32_e32 v13, v136, v38
	v_fmac_f32_e32 v14, v136, v42
	v_fmac_f32_e32 v15, v136, v46
	v_fmac_f32_e32 v0, v136, v54
	v_fmac_f32_e32 v8, v137, v51
	v_fmac_f32_e32 v9, v137, v23
	v_fmac_f32_e32 v10, v137, v27
	v_fmac_f32_e32 v11, v137, v31
	v_fmac_f32_e32 v12, v137, v35
	v_fmac_f32_e32 v13, v137, v39
	v_fmac_f32_e32 v14, v137, v43
	v_fmac_f32_e32 v15, v137, v47
	v_fmac_f32_e32 v0, v137, v55
	v_fmac_f32_e32 v8, v138, v52
	v_fmac_f32_e32 v9, v138, v24
	v_fmac_f32_e32 v10, v138, v28
	v_fmac_f32_e32 v11, v138, v32
	v_fmac_f32_e32 v12, v138, v36
	v_fmac_f32_e32 v13, v138, v40
	v_fmac_f32_e32 v14, v138, v44
	v_fmac_f32_e32 v15, v138, v48
	v_fmac_f32_e32 v0, v138, v56
	v_fmac_f32_e32 v8, v139, v53
	v_fmac_f32_e32 v9, v139, v25
	v_fmac_f32_e32 v10, v139, v29
	v_fmac_f32_e32 v11, v139, v33
	v_fmac_f32_e32 v12, v139, v37
	v_fmac_f32_e32 v13, v139, v41
	v_fmac_f32_e32 v14, v139, v45
	v_fmac_f32_e32 v15, v139, v49
	v_fmac_f32_e32 v0, v139, v57
	ds_read_b128 v[50:53], v5 offset:32
	ds_read_b128 v[22:25], v5 offset:4128
	ds_read_b128 v[26:29], v5 offset:8224
	ds_read_b128 v[30:33], v5 offset:12320
	ds_read_b128 v[34:37], v5 offset:16416
	ds_read_b128 v[38:41], v5 offset:20512
	ds_read_b128 v[42:45], v5 offset:24608
	ds_read_b128 v[46:49], v5 offset:28704
	ds_read_b128 v[54:57], v5 offset:32800
	s_waitcnt vmcnt(52) lgkmcnt(0)
	v_fmac_f32_e32 v8, v140, v50
	v_fmac_f32_e32 v9, v140, v22
	v_fmac_f32_e32 v10, v140, v26
	v_fmac_f32_e32 v11, v140, v30
	v_fmac_f32_e32 v12, v140, v34
	v_fmac_f32_e32 v13, v140, v38
	v_fmac_f32_e32 v14, v140, v42
	v_fmac_f32_e32 v15, v140, v46
	v_fmac_f32_e32 v0, v140, v54
	v_fmac_f32_e32 v8, v141, v51
	v_fmac_f32_e32 v9, v141, v23
	v_fmac_f32_e32 v10, v141, v27
	v_fmac_f32_e32 v11, v141, v31
	v_fmac_f32_e32 v12, v141, v35
	v_fmac_f32_e32 v13, v141, v39
	v_fmac_f32_e32 v14, v141, v43
	v_fmac_f32_e32 v15, v141, v47
	v_fmac_f32_e32 v0, v141, v55
	v_fmac_f32_e32 v8, v142, v52
	v_fmac_f32_e32 v9, v142, v24
	v_fmac_f32_e32 v10, v142, v28
	v_fmac_f32_e32 v11, v142, v32
	v_fmac_f32_e32 v12, v142, v36
	v_fmac_f32_e32 v13, v142, v40
	v_fmac_f32_e32 v14, v142, v44
	v_fmac_f32_e32 v15, v142, v48
	v_fmac_f32_e32 v0, v142, v56
	v_fmac_f32_e32 v8, v143, v53
	v_fmac_f32_e32 v9, v143, v25
	v_fmac_f32_e32 v10, v143, v29
	v_fmac_f32_e32 v11, v143, v33
	v_fmac_f32_e32 v12, v143, v37
	v_fmac_f32_e32 v13, v143, v41
	v_fmac_f32_e32 v14, v143, v45
	v_fmac_f32_e32 v15, v143, v49
	v_fmac_f32_e32 v0, v143, v57
	ds_read_b128 v[50:53], v5 offset:48
	ds_read_b128 v[22:25], v5 offset:4144
	ds_read_b128 v[26:29], v5 offset:8240
	ds_read_b128 v[30:33], v5 offset:12336
	ds_read_b128 v[34:37], v5 offset:16432
	ds_read_b128 v[38:41], v5 offset:20528
	ds_read_b128 v[42:45], v5 offset:24624
	ds_read_b128 v[46:49], v5 offset:28720
	ds_read_b128 v[54:57], v5 offset:32816
	s_waitcnt vmcnt(48) lgkmcnt(0)
	v_fmac_f32_e32 v8, v146, v50
	v_fmac_f32_e32 v9, v146, v22
	v_fmac_f32_e32 v10, v146, v26
	v_fmac_f32_e32 v11, v146, v30
	v_fmac_f32_e32 v12, v146, v34
	v_fmac_f32_e32 v13, v146, v38
	v_fmac_f32_e32 v14, v146, v42
	v_fmac_f32_e32 v15, v146, v46
	v_fmac_f32_e32 v0, v146, v54
	v_fmac_f32_e32 v8, v147, v51
	v_fmac_f32_e32 v9, v147, v23
	v_fmac_f32_e32 v10, v147, v27
	v_fmac_f32_e32 v11, v147, v31
	v_fmac_f32_e32 v12, v147, v35
	v_fmac_f32_e32 v13, v147, v39
	v_fmac_f32_e32 v14, v147, v43
	v_fmac_f32_e32 v15, v147, v47
	v_fmac_f32_e32 v0, v147, v55
	v_fmac_f32_e32 v8, v148, v52
	v_fmac_f32_e32 v9, v148, v24
	v_fmac_f32_e32 v10, v148, v28
	v_fmac_f32_e32 v11, v148, v32
	v_fmac_f32_e32 v12, v148, v36
	v_fmac_f32_e32 v13, v148, v40
	v_fmac_f32_e32 v14, v148, v44
	v_fmac_f32_e32 v15, v148, v48
	v_fmac_f32_e32 v0, v148, v56
	v_fmac_f32_e32 v8, v149, v53
	v_fmac_f32_e32 v9, v149, v25
	v_fmac_f32_e32 v10, v149, v29
	v_fmac_f32_e32 v11, v149, v33
	v_fmac_f32_e32 v12, v149, v37
	v_fmac_f32_e32 v13, v149, v41
	v_fmac_f32_e32 v14, v149, v45
	v_fmac_f32_e32 v15, v149, v49
	v_fmac_f32_e32 v0, v149, v57
	s_add_i32 s12, s12, 64
	global_load_dword v132, v68, s[24:25]
	s_add_u32 s24, s24, 0x6000
	s_addc_u32 s25, s25, 0
	global_load_dword v133, v68, s[24:25]
	s_add_u32 s24, s24, 0x6000
	s_addc_u32 s25, s25, 0
	global_load_dword v134, v68, s[24:25]
	s_add_u32 s24, s24, 0x6000
	s_addc_u32 s25, s25, 0
	global_load_dword v135, v68, s[24:25]
	s_add_u32 s24, s24, 0x6000
	s_addc_u32 s25, s25, 0
	global_load_dword v136, v68, s[24:25]
	s_add_u32 s24, s24, 0x6000
	s_addc_u32 s25, s25, 0
	global_load_dword v137, v68, s[24:25]
	s_add_u32 s24, s24, 0x6000
	s_addc_u32 s25, s25, 0
	global_load_dword v138, v68, s[24:25]
	s_add_u32 s24, s24, 0x6000
	s_addc_u32 s25, s25, 0
	global_load_dword v139, v68, s[24:25]
	s_add_u32 s24, s24, 0x6000
	s_addc_u32 s25, s25, 0
	global_load_dword v140, v68, s[24:25]
	s_add_u32 s24, s24, 0x6000
	s_addc_u32 s25, s25, 0
	global_load_dword v141, v68, s[24:25]
	s_add_u32 s24, s24, 0x6000
	s_addc_u32 s25, s25, 0
	global_load_dword v142, v68, s[24:25]
	s_add_u32 s24, s24, 0x6000
	s_addc_u32 s25, s25, 0
	global_load_dword v143, v68, s[24:25]
	s_add_u32 s24, s24, 0x6000
	s_addc_u32 s25, s25, 0
	global_load_dword v146, v68, s[24:25]
	s_add_u32 s24, s24, 0x6000
	s_addc_u32 s25, s25, 0
	global_load_dword v147, v68, s[24:25]
	s_add_u32 s24, s24, 0x6000
	s_addc_u32 s25, s25, 0
	global_load_dword v148, v68, s[24:25]
	s_add_u32 s24, s24, 0x6000
	s_addc_u32 s25, s25, 0
	global_load_dword v149, v68, s[24:25]
	s_add_u32 s24, s24, 0x6000
	s_addc_u32 s25, s25, 0
	v_mov_b32_e32 v5, s12
	ds_read_b128 v[50:53], v5
	ds_read_b128 v[22:25], v5 offset:4096
	ds_read_b128 v[26:29], v5 offset:8192
	ds_read_b128 v[30:33], v5 offset:12288
	ds_read_b128 v[34:37], v5 offset:16384
	ds_read_b128 v[38:41], v5 offset:20480
	ds_read_b128 v[42:45], v5 offset:24576
	ds_read_b128 v[46:49], v5 offset:28672
	ds_read_b128 v[54:57], v5 offset:32768
	s_waitcnt vmcnt(60) lgkmcnt(0)
	v_fmac_f32_e32 v8, v150, v50
	v_fmac_f32_e32 v9, v150, v22
	v_fmac_f32_e32 v10, v150, v26
	v_fmac_f32_e32 v11, v150, v30
	v_fmac_f32_e32 v12, v150, v34
	v_fmac_f32_e32 v13, v150, v38
	v_fmac_f32_e32 v14, v150, v42
	v_fmac_f32_e32 v15, v150, v46
	v_fmac_f32_e32 v0, v150, v54
	v_fmac_f32_e32 v8, v151, v51
	v_fmac_f32_e32 v9, v151, v23
	v_fmac_f32_e32 v10, v151, v27
	v_fmac_f32_e32 v11, v151, v31
	v_fmac_f32_e32 v12, v151, v35
	v_fmac_f32_e32 v13, v151, v39
	v_fmac_f32_e32 v14, v151, v43
	v_fmac_f32_e32 v15, v151, v47
	v_fmac_f32_e32 v0, v151, v55
	v_fmac_f32_e32 v8, v152, v52
	v_fmac_f32_e32 v9, v152, v24
	v_fmac_f32_e32 v10, v152, v28
	v_fmac_f32_e32 v11, v152, v32
	v_fmac_f32_e32 v12, v152, v36
	v_fmac_f32_e32 v13, v152, v40
	v_fmac_f32_e32 v14, v152, v44
	v_fmac_f32_e32 v15, v152, v48
	v_fmac_f32_e32 v0, v152, v56
	v_fmac_f32_e32 v8, v153, v53
	v_fmac_f32_e32 v9, v153, v25
	v_fmac_f32_e32 v10, v153, v29
	v_fmac_f32_e32 v11, v153, v33
	v_fmac_f32_e32 v12, v153, v37
	v_fmac_f32_e32 v13, v153, v41
	v_fmac_f32_e32 v14, v153, v45
	v_fmac_f32_e32 v15, v153, v49
	v_fmac_f32_e32 v0, v153, v57
	ds_read_b128 v[50:53], v5 offset:16
	ds_read_b128 v[22:25], v5 offset:4112
	ds_read_b128 v[26:29], v5 offset:8208
	ds_read_b128 v[30:33], v5 offset:12304
	ds_read_b128 v[34:37], v5 offset:16400
	ds_read_b128 v[38:41], v5 offset:20496
	ds_read_b128 v[42:45], v5 offset:24592
	ds_read_b128 v[46:49], v5 offset:28688
	ds_read_b128 v[54:57], v5 offset:32784
	s_waitcnt vmcnt(56) lgkmcnt(0)
	v_fmac_f32_e32 v8, v154, v50
	v_fmac_f32_e32 v9, v154, v22
	v_fmac_f32_e32 v10, v154, v26
	v_fmac_f32_e32 v11, v154, v30
	v_fmac_f32_e32 v12, v154, v34
	v_fmac_f32_e32 v13, v154, v38
	v_fmac_f32_e32 v14, v154, v42
	v_fmac_f32_e32 v15, v154, v46
	v_fmac_f32_e32 v0, v154, v54
	v_fmac_f32_e32 v8, v155, v51
	v_fmac_f32_e32 v9, v155, v23
	v_fmac_f32_e32 v10, v155, v27
	v_fmac_f32_e32 v11, v155, v31
	v_fmac_f32_e32 v12, v155, v35
	v_fmac_f32_e32 v13, v155, v39
	v_fmac_f32_e32 v14, v155, v43
	v_fmac_f32_e32 v15, v155, v47
	v_fmac_f32_e32 v0, v155, v55
	v_fmac_f32_e32 v8, v156, v52
	v_fmac_f32_e32 v9, v156, v24
	v_fmac_f32_e32 v10, v156, v28
	v_fmac_f32_e32 v11, v156, v32
	v_fmac_f32_e32 v12, v156, v36
	v_fmac_f32_e32 v13, v156, v40
	v_fmac_f32_e32 v14, v156, v44
	v_fmac_f32_e32 v15, v156, v48
	v_fmac_f32_e32 v0, v156, v56
	v_fmac_f32_e32 v8, v157, v53
	v_fmac_f32_e32 v9, v157, v25
	v_fmac_f32_e32 v10, v157, v29
	v_fmac_f32_e32 v11, v157, v33
	v_fmac_f32_e32 v12, v157, v37
	v_fmac_f32_e32 v13, v157, v41
	v_fmac_f32_e32 v14, v157, v45
	v_fmac_f32_e32 v15, v157, v49
	v_fmac_f32_e32 v0, v157, v57
	ds_read_b128 v[50:53], v5 offset:32
	ds_read_b128 v[22:25], v5 offset:4128
	ds_read_b128 v[26:29], v5 offset:8224
	ds_read_b128 v[30:33], v5 offset:12320
	ds_read_b128 v[34:37], v5 offset:16416
	ds_read_b128 v[38:41], v5 offset:20512
	ds_read_b128 v[42:45], v5 offset:24608
	ds_read_b128 v[46:49], v5 offset:28704
	ds_read_b128 v[54:57], v5 offset:32800
	s_waitcnt vmcnt(52) lgkmcnt(0)
	v_fmac_f32_e32 v8, v158, v50
	v_fmac_f32_e32 v9, v158, v22
	v_fmac_f32_e32 v10, v158, v26
	v_fmac_f32_e32 v11, v158, v30
	v_fmac_f32_e32 v12, v158, v34
	v_fmac_f32_e32 v13, v158, v38
	v_fmac_f32_e32 v14, v158, v42
	v_fmac_f32_e32 v15, v158, v46
	v_fmac_f32_e32 v0, v158, v54
	v_fmac_f32_e32 v8, v159, v51
	v_fmac_f32_e32 v9, v159, v23
	v_fmac_f32_e32 v10, v159, v27
	v_fmac_f32_e32 v11, v159, v31
	v_fmac_f32_e32 v12, v159, v35
	v_fmac_f32_e32 v13, v159, v39
	v_fmac_f32_e32 v14, v159, v43
	v_fmac_f32_e32 v15, v159, v47
	v_fmac_f32_e32 v0, v159, v55
	v_fmac_f32_e32 v8, v160, v52
	v_fmac_f32_e32 v9, v160, v24
	v_fmac_f32_e32 v10, v160, v28
	v_fmac_f32_e32 v11, v160, v32
	v_fmac_f32_e32 v12, v160, v36
	v_fmac_f32_e32 v13, v160, v40
	v_fmac_f32_e32 v14, v160, v44
	v_fmac_f32_e32 v15, v160, v48
	v_fmac_f32_e32 v0, v160, v56
	v_fmac_f32_e32 v8, v161, v53
	v_fmac_f32_e32 v9, v161, v25
	v_fmac_f32_e32 v10, v161, v29
	v_fmac_f32_e32 v11, v161, v33
	v_fmac_f32_e32 v12, v161, v37
	v_fmac_f32_e32 v13, v161, v41
	v_fmac_f32_e32 v14, v161, v45
	v_fmac_f32_e32 v15, v161, v49
	v_fmac_f32_e32 v0, v161, v57
	ds_read_b128 v[50:53], v5 offset:48
	ds_read_b128 v[22:25], v5 offset:4144
	ds_read_b128 v[26:29], v5 offset:8240
	ds_read_b128 v[30:33], v5 offset:12336
	ds_read_b128 v[34:37], v5 offset:16432
	ds_read_b128 v[38:41], v5 offset:20528
	ds_read_b128 v[42:45], v5 offset:24624
	ds_read_b128 v[46:49], v5 offset:28720
	ds_read_b128 v[54:57], v5 offset:32816
	s_waitcnt vmcnt(48) lgkmcnt(0)
	v_fmac_f32_e32 v8, v162, v50
	v_fmac_f32_e32 v9, v162, v22
	v_fmac_f32_e32 v10, v162, v26
	v_fmac_f32_e32 v11, v162, v30
	v_fmac_f32_e32 v12, v162, v34
	v_fmac_f32_e32 v13, v162, v38
	v_fmac_f32_e32 v14, v162, v42
	v_fmac_f32_e32 v15, v162, v46
	v_fmac_f32_e32 v0, v162, v54
	v_fmac_f32_e32 v8, v163, v51
	v_fmac_f32_e32 v9, v163, v23
	v_fmac_f32_e32 v10, v163, v27
	v_fmac_f32_e32 v11, v163, v31
	v_fmac_f32_e32 v12, v163, v35
	v_fmac_f32_e32 v13, v163, v39
	v_fmac_f32_e32 v14, v163, v43
	v_fmac_f32_e32 v15, v163, v47
	v_fmac_f32_e32 v0, v163, v55
	v_fmac_f32_e32 v8, v164, v52
	v_fmac_f32_e32 v9, v164, v24
	v_fmac_f32_e32 v10, v164, v28
	v_fmac_f32_e32 v11, v164, v32
	v_fmac_f32_e32 v12, v164, v36
	v_fmac_f32_e32 v13, v164, v40
	v_fmac_f32_e32 v14, v164, v44
	v_fmac_f32_e32 v15, v164, v48
	v_fmac_f32_e32 v0, v164, v56
	v_fmac_f32_e32 v8, v165, v53
	v_fmac_f32_e32 v9, v165, v25
	v_fmac_f32_e32 v10, v165, v29
	v_fmac_f32_e32 v11, v165, v33
	v_fmac_f32_e32 v12, v165, v37
	v_fmac_f32_e32 v13, v165, v41
	v_fmac_f32_e32 v14, v165, v45
	v_fmac_f32_e32 v15, v165, v49
	v_fmac_f32_e32 v0, v165, v57
	s_add_i32 s12, s12, 64
	global_load_dword v150, v68, s[24:25]
	s_add_u32 s24, s24, 0x6000
	s_addc_u32 s25, s25, 0
	global_load_dword v151, v68, s[24:25]
	s_add_u32 s24, s24, 0x6000
	s_addc_u32 s25, s25, 0
	global_load_dword v152, v68, s[24:25]
	s_add_u32 s24, s24, 0x6000
	s_addc_u32 s25, s25, 0
	global_load_dword v153, v68, s[24:25]
	s_add_u32 s24, s24, 0x6000
	s_addc_u32 s25, s25, 0
	global_load_dword v154, v68, s[24:25]
	s_add_u32 s24, s24, 0x6000
	s_addc_u32 s25, s25, 0
	global_load_dword v155, v68, s[24:25]
	s_add_u32 s24, s24, 0x6000
	s_addc_u32 s25, s25, 0
	global_load_dword v156, v68, s[24:25]
	s_add_u32 s24, s24, 0x6000
	s_addc_u32 s25, s25, 0
	global_load_dword v157, v68, s[24:25]
	s_add_u32 s24, s24, 0x6000
	s_addc_u32 s25, s25, 0
	global_load_dword v158, v68, s[24:25]
	s_add_u32 s24, s24, 0x6000
	s_addc_u32 s25, s25, 0
	global_load_dword v159, v68, s[24:25]
	s_add_u32 s24, s24, 0x6000
	s_addc_u32 s25, s25, 0
	global_load_dword v160, v68, s[24:25]
	s_add_u32 s24, s24, 0x6000
	s_addc_u32 s25, s25, 0
	global_load_dword v161, v68, s[24:25]
	s_add_u32 s24, s24, 0x6000
	s_addc_u32 s25, s25, 0
	global_load_dword v162, v68, s[24:25]
	s_add_u32 s24, s24, 0x6000
	s_addc_u32 s25, s25, 0
	global_load_dword v163, v68, s[24:25]
	s_add_u32 s24, s24, 0x6000
	s_addc_u32 s25, s25, 0
	global_load_dword v164, v68, s[24:25]
	s_add_u32 s24, s24, 0x6000
	s_addc_u32 s25, s25, 0
	global_load_dword v165, v68, s[24:25]
	v_mov_b32_e32 v5, s12
	ds_read_b128 v[50:53], v5
	ds_read_b128 v[22:25], v5 offset:4096
	ds_read_b128 v[26:29], v5 offset:8192
	ds_read_b128 v[30:33], v5 offset:12288
	ds_read_b128 v[34:37], v5 offset:16384
	ds_read_b128 v[38:41], v5 offset:20480
	ds_read_b128 v[42:45], v5 offset:24576
	ds_read_b128 v[46:49], v5 offset:28672
	ds_read_b128 v[54:57], v5 offset:32768
	s_waitcnt vmcnt(60) lgkmcnt(0)
	v_fmac_f32_e32 v8, v100, v50
	v_fmac_f32_e32 v9, v100, v22
	v_fmac_f32_e32 v10, v100, v26
	v_fmac_f32_e32 v11, v100, v30
	v_fmac_f32_e32 v12, v100, v34
	v_fmac_f32_e32 v13, v100, v38
	v_fmac_f32_e32 v14, v100, v42
	v_fmac_f32_e32 v15, v100, v46
	v_fmac_f32_e32 v0, v100, v54
	v_fmac_f32_e32 v8, v101, v51
	v_fmac_f32_e32 v9, v101, v23
	v_fmac_f32_e32 v10, v101, v27
	v_fmac_f32_e32 v11, v101, v31
	v_fmac_f32_e32 v12, v101, v35
	v_fmac_f32_e32 v13, v101, v39
	v_fmac_f32_e32 v14, v101, v43
	v_fmac_f32_e32 v15, v101, v47
	v_fmac_f32_e32 v0, v101, v55
	v_fmac_f32_e32 v8, v102, v52
	v_fmac_f32_e32 v9, v102, v24
	v_fmac_f32_e32 v10, v102, v28
	v_fmac_f32_e32 v11, v102, v32
	v_fmac_f32_e32 v12, v102, v36
	v_fmac_f32_e32 v13, v102, v40
	v_fmac_f32_e32 v14, v102, v44
	v_fmac_f32_e32 v15, v102, v48
	v_fmac_f32_e32 v0, v102, v56
	v_fmac_f32_e32 v8, v103, v53
	v_fmac_f32_e32 v9, v103, v25
	v_fmac_f32_e32 v10, v103, v29
	v_fmac_f32_e32 v11, v103, v33
	v_fmac_f32_e32 v12, v103, v37
	v_fmac_f32_e32 v13, v103, v41
	v_fmac_f32_e32 v14, v103, v45
	v_fmac_f32_e32 v15, v103, v49
	v_fmac_f32_e32 v0, v103, v57
	ds_read_b128 v[50:53], v5 offset:16
	ds_read_b128 v[22:25], v5 offset:4112
	ds_read_b128 v[26:29], v5 offset:8208
	ds_read_b128 v[30:33], v5 offset:12304
	ds_read_b128 v[34:37], v5 offset:16400
	ds_read_b128 v[38:41], v5 offset:20496
	ds_read_b128 v[42:45], v5 offset:24592
	ds_read_b128 v[46:49], v5 offset:28688
	ds_read_b128 v[54:57], v5 offset:32784
	s_waitcnt vmcnt(56) lgkmcnt(0)
	v_fmac_f32_e32 v8, v104, v50
	v_fmac_f32_e32 v9, v104, v22
	v_fmac_f32_e32 v10, v104, v26
	v_fmac_f32_e32 v11, v104, v30
	v_fmac_f32_e32 v12, v104, v34
	v_fmac_f32_e32 v13, v104, v38
	v_fmac_f32_e32 v14, v104, v42
	v_fmac_f32_e32 v15, v104, v46
	v_fmac_f32_e32 v0, v104, v54
	v_fmac_f32_e32 v8, v105, v51
	v_fmac_f32_e32 v9, v105, v23
	v_fmac_f32_e32 v10, v105, v27
	v_fmac_f32_e32 v11, v105, v31
	v_fmac_f32_e32 v12, v105, v35
	v_fmac_f32_e32 v13, v105, v39
	v_fmac_f32_e32 v14, v105, v43
	v_fmac_f32_e32 v15, v105, v47
	v_fmac_f32_e32 v0, v105, v55
	v_fmac_f32_e32 v8, v106, v52
	v_fmac_f32_e32 v9, v106, v24
	v_fmac_f32_e32 v10, v106, v28
	v_fmac_f32_e32 v11, v106, v32
	v_fmac_f32_e32 v12, v106, v36
	v_fmac_f32_e32 v13, v106, v40
	v_fmac_f32_e32 v14, v106, v44
	v_fmac_f32_e32 v15, v106, v48
	v_fmac_f32_e32 v0, v106, v56
	v_fmac_f32_e32 v8, v107, v53
	v_fmac_f32_e32 v9, v107, v25
	v_fmac_f32_e32 v10, v107, v29
	v_fmac_f32_e32 v11, v107, v33
	v_fmac_f32_e32 v12, v107, v37
	v_fmac_f32_e32 v13, v107, v41
	v_fmac_f32_e32 v14, v107, v45
	v_fmac_f32_e32 v15, v107, v49
	v_fmac_f32_e32 v0, v107, v57
	ds_read_b128 v[50:53], v5 offset:32
	ds_read_b128 v[22:25], v5 offset:4128
	ds_read_b128 v[26:29], v5 offset:8224
	ds_read_b128 v[30:33], v5 offset:12320
	ds_read_b128 v[34:37], v5 offset:16416
	ds_read_b128 v[38:41], v5 offset:20512
	ds_read_b128 v[42:45], v5 offset:24608
	ds_read_b128 v[46:49], v5 offset:28704
	ds_read_b128 v[54:57], v5 offset:32800
	s_waitcnt vmcnt(52) lgkmcnt(0)
	v_fmac_f32_e32 v8, v108, v50
	v_fmac_f32_e32 v9, v108, v22
	v_fmac_f32_e32 v10, v108, v26
	v_fmac_f32_e32 v11, v108, v30
	v_fmac_f32_e32 v12, v108, v34
	v_fmac_f32_e32 v13, v108, v38
	v_fmac_f32_e32 v14, v108, v42
	v_fmac_f32_e32 v15, v108, v46
	v_fmac_f32_e32 v0, v108, v54
	v_fmac_f32_e32 v8, v109, v51
	v_fmac_f32_e32 v9, v109, v23
	v_fmac_f32_e32 v10, v109, v27
	v_fmac_f32_e32 v11, v109, v31
	v_fmac_f32_e32 v12, v109, v35
	v_fmac_f32_e32 v13, v109, v39
	v_fmac_f32_e32 v14, v109, v43
	v_fmac_f32_e32 v15, v109, v47
	v_fmac_f32_e32 v0, v109, v55
	v_fmac_f32_e32 v8, v110, v52
	v_fmac_f32_e32 v9, v110, v24
	v_fmac_f32_e32 v10, v110, v28
	v_fmac_f32_e32 v11, v110, v32
	v_fmac_f32_e32 v12, v110, v36
	v_fmac_f32_e32 v13, v110, v40
	v_fmac_f32_e32 v14, v110, v44
	v_fmac_f32_e32 v15, v110, v48
	v_fmac_f32_e32 v0, v110, v56
	v_fmac_f32_e32 v8, v111, v53
	v_fmac_f32_e32 v9, v111, v25
	v_fmac_f32_e32 v10, v111, v29
	v_fmac_f32_e32 v11, v111, v33
	v_fmac_f32_e32 v12, v111, v37
	v_fmac_f32_e32 v13, v111, v41
	v_fmac_f32_e32 v14, v111, v45
	v_fmac_f32_e32 v15, v111, v49
	v_fmac_f32_e32 v0, v111, v57
	ds_read_b128 v[50:53], v5 offset:48
	ds_read_b128 v[22:25], v5 offset:4144
	ds_read_b128 v[26:29], v5 offset:8240
	ds_read_b128 v[30:33], v5 offset:12336
	ds_read_b128 v[34:37], v5 offset:16432
	ds_read_b128 v[38:41], v5 offset:20528
	ds_read_b128 v[42:45], v5 offset:24624
	ds_read_b128 v[46:49], v5 offset:28720
	ds_read_b128 v[54:57], v5 offset:32816
	s_waitcnt vmcnt(48) lgkmcnt(0)
	v_fmac_f32_e32 v8, v112, v50
	v_fmac_f32_e32 v9, v112, v22
	v_fmac_f32_e32 v10, v112, v26
	v_fmac_f32_e32 v11, v112, v30
	v_fmac_f32_e32 v12, v112, v34
	v_fmac_f32_e32 v13, v112, v38
	v_fmac_f32_e32 v14, v112, v42
	v_fmac_f32_e32 v15, v112, v46
	v_fmac_f32_e32 v0, v112, v54
	v_fmac_f32_e32 v8, v113, v51
	v_fmac_f32_e32 v9, v113, v23
	v_fmac_f32_e32 v10, v113, v27
	v_fmac_f32_e32 v11, v113, v31
	v_fmac_f32_e32 v12, v113, v35
	v_fmac_f32_e32 v13, v113, v39
	v_fmac_f32_e32 v14, v113, v43
	v_fmac_f32_e32 v15, v113, v47
	v_fmac_f32_e32 v0, v113, v55
	v_fmac_f32_e32 v8, v114, v52
	v_fmac_f32_e32 v9, v114, v24
	v_fmac_f32_e32 v10, v114, v28
	v_fmac_f32_e32 v11, v114, v32
	v_fmac_f32_e32 v12, v114, v36
	v_fmac_f32_e32 v13, v114, v40
	v_fmac_f32_e32 v14, v114, v44
	v_fmac_f32_e32 v15, v114, v48
	v_fmac_f32_e32 v0, v114, v56
	v_fmac_f32_e32 v8, v115, v53
	v_fmac_f32_e32 v9, v115, v25
	v_fmac_f32_e32 v10, v115, v29
	v_fmac_f32_e32 v11, v115, v33
	v_fmac_f32_e32 v12, v115, v37
	v_fmac_f32_e32 v13, v115, v41
	v_fmac_f32_e32 v14, v115, v45
	v_fmac_f32_e32 v15, v115, v49
	v_fmac_f32_e32 v0, v115, v57
	s_add_i32 s12, s12, 64
	v_mov_b32_e32 v5, s12
	ds_read_b128 v[50:53], v5
	ds_read_b128 v[22:25], v5 offset:4096
	ds_read_b128 v[26:29], v5 offset:8192
	ds_read_b128 v[30:33], v5 offset:12288
	ds_read_b128 v[34:37], v5 offset:16384
	ds_read_b128 v[38:41], v5 offset:20480
	ds_read_b128 v[42:45], v5 offset:24576
	ds_read_b128 v[46:49], v5 offset:28672
	ds_read_b128 v[54:57], v5 offset:32768
	s_waitcnt vmcnt(44) lgkmcnt(0)
	v_fmac_f32_e32 v8, v116, v50
	v_fmac_f32_e32 v9, v116, v22
	v_fmac_f32_e32 v10, v116, v26
	v_fmac_f32_e32 v11, v116, v30
	v_fmac_f32_e32 v12, v116, v34
	v_fmac_f32_e32 v13, v116, v38
	v_fmac_f32_e32 v14, v116, v42
	v_fmac_f32_e32 v15, v116, v46
	v_fmac_f32_e32 v0, v116, v54
	v_fmac_f32_e32 v8, v117, v51
	v_fmac_f32_e32 v9, v117, v23
	v_fmac_f32_e32 v10, v117, v27
	v_fmac_f32_e32 v11, v117, v31
	v_fmac_f32_e32 v12, v117, v35
	v_fmac_f32_e32 v13, v117, v39
	v_fmac_f32_e32 v14, v117, v43
	v_fmac_f32_e32 v15, v117, v47
	v_fmac_f32_e32 v0, v117, v55
	v_fmac_f32_e32 v8, v118, v52
	v_fmac_f32_e32 v9, v118, v24
	v_fmac_f32_e32 v10, v118, v28
	v_fmac_f32_e32 v11, v118, v32
	v_fmac_f32_e32 v12, v118, v36
	v_fmac_f32_e32 v13, v118, v40
	v_fmac_f32_e32 v14, v118, v44
	v_fmac_f32_e32 v15, v118, v48
	v_fmac_f32_e32 v0, v118, v56
	v_fmac_f32_e32 v8, v119, v53
	v_fmac_f32_e32 v9, v119, v25
	v_fmac_f32_e32 v10, v119, v29
	v_fmac_f32_e32 v11, v119, v33
	v_fmac_f32_e32 v12, v119, v37
	v_fmac_f32_e32 v13, v119, v41
	v_fmac_f32_e32 v14, v119, v45
	v_fmac_f32_e32 v15, v119, v49
	v_fmac_f32_e32 v0, v119, v57
	ds_read_b128 v[50:53], v5 offset:16
	ds_read_b128 v[22:25], v5 offset:4112
	ds_read_b128 v[26:29], v5 offset:8208
	ds_read_b128 v[30:33], v5 offset:12304
	ds_read_b128 v[34:37], v5 offset:16400
	ds_read_b128 v[38:41], v5 offset:20496
	ds_read_b128 v[42:45], v5 offset:24592
	ds_read_b128 v[46:49], v5 offset:28688
	ds_read_b128 v[54:57], v5 offset:32784
	s_waitcnt vmcnt(40) lgkmcnt(0)
	v_fmac_f32_e32 v8, v120, v50
	v_fmac_f32_e32 v9, v120, v22
	v_fmac_f32_e32 v10, v120, v26
	v_fmac_f32_e32 v11, v120, v30
	v_fmac_f32_e32 v12, v120, v34
	v_fmac_f32_e32 v13, v120, v38
	v_fmac_f32_e32 v14, v120, v42
	v_fmac_f32_e32 v15, v120, v46
	v_fmac_f32_e32 v0, v120, v54
	v_fmac_f32_e32 v8, v121, v51
	v_fmac_f32_e32 v9, v121, v23
	v_fmac_f32_e32 v10, v121, v27
	v_fmac_f32_e32 v11, v121, v31
	v_fmac_f32_e32 v12, v121, v35
	v_fmac_f32_e32 v13, v121, v39
	v_fmac_f32_e32 v14, v121, v43
	v_fmac_f32_e32 v15, v121, v47
	v_fmac_f32_e32 v0, v121, v55
	v_fmac_f32_e32 v8, v122, v52
	v_fmac_f32_e32 v9, v122, v24
	v_fmac_f32_e32 v10, v122, v28
	v_fmac_f32_e32 v11, v122, v32
	v_fmac_f32_e32 v12, v122, v36
	v_fmac_f32_e32 v13, v122, v40
	v_fmac_f32_e32 v14, v122, v44
	v_fmac_f32_e32 v15, v122, v48
	v_fmac_f32_e32 v0, v122, v56
	v_fmac_f32_e32 v8, v123, v53
	v_fmac_f32_e32 v9, v123, v25
	v_fmac_f32_e32 v10, v123, v29
	v_fmac_f32_e32 v11, v123, v33
	v_fmac_f32_e32 v12, v123, v37
	v_fmac_f32_e32 v13, v123, v41
	v_fmac_f32_e32 v14, v123, v45
	v_fmac_f32_e32 v15, v123, v49
	v_fmac_f32_e32 v0, v123, v57
	ds_read_b128 v[50:53], v5 offset:32
	ds_read_b128 v[22:25], v5 offset:4128
	ds_read_b128 v[26:29], v5 offset:8224
	ds_read_b128 v[30:33], v5 offset:12320
	ds_read_b128 v[34:37], v5 offset:16416
	ds_read_b128 v[38:41], v5 offset:20512
	ds_read_b128 v[42:45], v5 offset:24608
	ds_read_b128 v[46:49], v5 offset:28704
	ds_read_b128 v[54:57], v5 offset:32800
	s_waitcnt vmcnt(36) lgkmcnt(0)
	v_fmac_f32_e32 v8, v124, v50
	v_fmac_f32_e32 v9, v124, v22
	v_fmac_f32_e32 v10, v124, v26
	v_fmac_f32_e32 v11, v124, v30
	v_fmac_f32_e32 v12, v124, v34
	v_fmac_f32_e32 v13, v124, v38
	v_fmac_f32_e32 v14, v124, v42
	v_fmac_f32_e32 v15, v124, v46
	v_fmac_f32_e32 v0, v124, v54
	v_fmac_f32_e32 v8, v125, v51
	v_fmac_f32_e32 v9, v125, v23
	v_fmac_f32_e32 v10, v125, v27
	v_fmac_f32_e32 v11, v125, v31
	v_fmac_f32_e32 v12, v125, v35
	v_fmac_f32_e32 v13, v125, v39
	v_fmac_f32_e32 v14, v125, v43
	v_fmac_f32_e32 v15, v125, v47
	v_fmac_f32_e32 v0, v125, v55
	v_fmac_f32_e32 v8, v126, v52
	v_fmac_f32_e32 v9, v126, v24
	v_fmac_f32_e32 v10, v126, v28
	v_fmac_f32_e32 v11, v126, v32
	v_fmac_f32_e32 v12, v126, v36
	v_fmac_f32_e32 v13, v126, v40
	v_fmac_f32_e32 v14, v126, v44
	v_fmac_f32_e32 v15, v126, v48
	v_fmac_f32_e32 v0, v126, v56
	v_fmac_f32_e32 v8, v127, v53
	v_fmac_f32_e32 v9, v127, v25
	v_fmac_f32_e32 v10, v127, v29
	v_fmac_f32_e32 v11, v127, v33
	v_fmac_f32_e32 v12, v127, v37
	v_fmac_f32_e32 v13, v127, v41
	v_fmac_f32_e32 v14, v127, v45
	v_fmac_f32_e32 v15, v127, v49
	v_fmac_f32_e32 v0, v127, v57
	ds_read_b128 v[50:53], v5 offset:48
	ds_read_b128 v[22:25], v5 offset:4144
	ds_read_b128 v[26:29], v5 offset:8240
	ds_read_b128 v[30:33], v5 offset:12336
	ds_read_b128 v[34:37], v5 offset:16432
	ds_read_b128 v[38:41], v5 offset:20528
	ds_read_b128 v[42:45], v5 offset:24624
	ds_read_b128 v[46:49], v5 offset:28720
	ds_read_b128 v[54:57], v5 offset:32816
	s_waitcnt vmcnt(32) lgkmcnt(0)
	v_fmac_f32_e32 v8, v128, v50
	v_fmac_f32_e32 v9, v128, v22
	v_fmac_f32_e32 v10, v128, v26
	v_fmac_f32_e32 v11, v128, v30
	v_fmac_f32_e32 v12, v128, v34
	v_fmac_f32_e32 v13, v128, v38
	v_fmac_f32_e32 v14, v128, v42
	v_fmac_f32_e32 v15, v128, v46
	v_fmac_f32_e32 v0, v128, v54
	v_fmac_f32_e32 v8, v129, v51
	v_fmac_f32_e32 v9, v129, v23
	v_fmac_f32_e32 v10, v129, v27
	v_fmac_f32_e32 v11, v129, v31
	v_fmac_f32_e32 v12, v129, v35
	v_fmac_f32_e32 v13, v129, v39
	v_fmac_f32_e32 v14, v129, v43
	v_fmac_f32_e32 v15, v129, v47
	v_fmac_f32_e32 v0, v129, v55
	v_fmac_f32_e32 v8, v130, v52
	v_fmac_f32_e32 v9, v130, v24
	v_fmac_f32_e32 v10, v130, v28
	v_fmac_f32_e32 v11, v130, v32
	v_fmac_f32_e32 v12, v130, v36
	v_fmac_f32_e32 v13, v130, v40
	v_fmac_f32_e32 v14, v130, v44
	v_fmac_f32_e32 v15, v130, v48
	v_fmac_f32_e32 v0, v130, v56
	v_fmac_f32_e32 v8, v131, v53
	v_fmac_f32_e32 v9, v131, v25
	v_fmac_f32_e32 v10, v131, v29
	v_fmac_f32_e32 v11, v131, v33
	v_fmac_f32_e32 v12, v131, v37
	v_fmac_f32_e32 v13, v131, v41
	v_fmac_f32_e32 v14, v131, v45
	v_fmac_f32_e32 v15, v131, v49
	v_fmac_f32_e32 v0, v131, v57
	s_add_i32 s12, s12, 64
	v_mov_b32_e32 v5, s12
	ds_read_b128 v[50:53], v5
	ds_read_b128 v[22:25], v5 offset:4096
	ds_read_b128 v[26:29], v5 offset:8192
	ds_read_b128 v[30:33], v5 offset:12288
	ds_read_b128 v[34:37], v5 offset:16384
	ds_read_b128 v[38:41], v5 offset:20480
	ds_read_b128 v[42:45], v5 offset:24576
	ds_read_b128 v[46:49], v5 offset:28672
	ds_read_b128 v[54:57], v5 offset:32768
	s_waitcnt vmcnt(28) lgkmcnt(0)
	v_fmac_f32_e32 v8, v132, v50
	v_fmac_f32_e32 v9, v132, v22
	v_fmac_f32_e32 v10, v132, v26
	v_fmac_f32_e32 v11, v132, v30
	v_fmac_f32_e32 v12, v132, v34
	v_fmac_f32_e32 v13, v132, v38
	v_fmac_f32_e32 v14, v132, v42
	v_fmac_f32_e32 v15, v132, v46
	v_fmac_f32_e32 v0, v132, v54
	v_fmac_f32_e32 v8, v133, v51
	v_fmac_f32_e32 v9, v133, v23
	v_fmac_f32_e32 v10, v133, v27
	v_fmac_f32_e32 v11, v133, v31
	v_fmac_f32_e32 v12, v133, v35
	v_fmac_f32_e32 v13, v133, v39
	v_fmac_f32_e32 v14, v133, v43
	v_fmac_f32_e32 v15, v133, v47
	v_fmac_f32_e32 v0, v133, v55
	v_fmac_f32_e32 v8, v134, v52
	v_fmac_f32_e32 v9, v134, v24
	v_fmac_f32_e32 v10, v134, v28
	v_fmac_f32_e32 v11, v134, v32
	v_fmac_f32_e32 v12, v134, v36
	v_fmac_f32_e32 v13, v134, v40
	v_fmac_f32_e32 v14, v134, v44
	v_fmac_f32_e32 v15, v134, v48
	v_fmac_f32_e32 v0, v134, v56
	v_fmac_f32_e32 v8, v135, v53
	v_fmac_f32_e32 v9, v135, v25
	v_fmac_f32_e32 v10, v135, v29
	v_fmac_f32_e32 v11, v135, v33
	v_fmac_f32_e32 v12, v135, v37
	v_fmac_f32_e32 v13, v135, v41
	v_fmac_f32_e32 v14, v135, v45
	v_fmac_f32_e32 v15, v135, v49
	v_fmac_f32_e32 v0, v135, v57
	ds_read_b128 v[50:53], v5 offset:16
	ds_read_b128 v[22:25], v5 offset:4112
	ds_read_b128 v[26:29], v5 offset:8208
	ds_read_b128 v[30:33], v5 offset:12304
	ds_read_b128 v[34:37], v5 offset:16400
	ds_read_b128 v[38:41], v5 offset:20496
	ds_read_b128 v[42:45], v5 offset:24592
	ds_read_b128 v[46:49], v5 offset:28688
	ds_read_b128 v[54:57], v5 offset:32784
	s_waitcnt vmcnt(24) lgkmcnt(0)
	v_fmac_f32_e32 v8, v136, v50
	v_fmac_f32_e32 v9, v136, v22
	v_fmac_f32_e32 v10, v136, v26
	v_fmac_f32_e32 v11, v136, v30
	v_fmac_f32_e32 v12, v136, v34
	v_fmac_f32_e32 v13, v136, v38
	v_fmac_f32_e32 v14, v136, v42
	v_fmac_f32_e32 v15, v136, v46
	v_fmac_f32_e32 v0, v136, v54
	v_fmac_f32_e32 v8, v137, v51
	v_fmac_f32_e32 v9, v137, v23
	v_fmac_f32_e32 v10, v137, v27
	v_fmac_f32_e32 v11, v137, v31
	v_fmac_f32_e32 v12, v137, v35
	v_fmac_f32_e32 v13, v137, v39
	v_fmac_f32_e32 v14, v137, v43
	v_fmac_f32_e32 v15, v137, v47
	v_fmac_f32_e32 v0, v137, v55
	v_fmac_f32_e32 v8, v138, v52
	v_fmac_f32_e32 v9, v138, v24
	v_fmac_f32_e32 v10, v138, v28
	v_fmac_f32_e32 v11, v138, v32
	v_fmac_f32_e32 v12, v138, v36
	v_fmac_f32_e32 v13, v138, v40
	v_fmac_f32_e32 v14, v138, v44
	v_fmac_f32_e32 v15, v138, v48
	v_fmac_f32_e32 v0, v138, v56
	v_fmac_f32_e32 v8, v139, v53
	v_fmac_f32_e32 v9, v139, v25
	v_fmac_f32_e32 v10, v139, v29
	v_fmac_f32_e32 v11, v139, v33
	v_fmac_f32_e32 v12, v139, v37
	v_fmac_f32_e32 v13, v139, v41
	v_fmac_f32_e32 v14, v139, v45
	v_fmac_f32_e32 v15, v139, v49
	v_fmac_f32_e32 v0, v139, v57
	ds_read_b128 v[50:53], v5 offset:32
	ds_read_b128 v[22:25], v5 offset:4128
	ds_read_b128 v[26:29], v5 offset:8224
	ds_read_b128 v[30:33], v5 offset:12320
	ds_read_b128 v[34:37], v5 offset:16416
	ds_read_b128 v[38:41], v5 offset:20512
	ds_read_b128 v[42:45], v5 offset:24608
	ds_read_b128 v[46:49], v5 offset:28704
	ds_read_b128 v[54:57], v5 offset:32800
	s_waitcnt vmcnt(20) lgkmcnt(0)
	v_fmac_f32_e32 v8, v140, v50
	v_fmac_f32_e32 v9, v140, v22
	v_fmac_f32_e32 v10, v140, v26
	v_fmac_f32_e32 v11, v140, v30
	v_fmac_f32_e32 v12, v140, v34
	v_fmac_f32_e32 v13, v140, v38
	v_fmac_f32_e32 v14, v140, v42
	v_fmac_f32_e32 v15, v140, v46
	v_fmac_f32_e32 v0, v140, v54
	v_fmac_f32_e32 v8, v141, v51
	v_fmac_f32_e32 v9, v141, v23
	v_fmac_f32_e32 v10, v141, v27
	v_fmac_f32_e32 v11, v141, v31
	v_fmac_f32_e32 v12, v141, v35
	v_fmac_f32_e32 v13, v141, v39
	v_fmac_f32_e32 v14, v141, v43
	v_fmac_f32_e32 v15, v141, v47
	v_fmac_f32_e32 v0, v141, v55
	v_fmac_f32_e32 v8, v142, v52
	v_fmac_f32_e32 v9, v142, v24
	v_fmac_f32_e32 v10, v142, v28
	v_fmac_f32_e32 v11, v142, v32
	v_fmac_f32_e32 v12, v142, v36
	v_fmac_f32_e32 v13, v142, v40
	v_fmac_f32_e32 v14, v142, v44
	v_fmac_f32_e32 v15, v142, v48
	v_fmac_f32_e32 v0, v142, v56
	v_fmac_f32_e32 v8, v143, v53
	v_fmac_f32_e32 v9, v143, v25
	v_fmac_f32_e32 v10, v143, v29
	v_fmac_f32_e32 v11, v143, v33
	v_fmac_f32_e32 v12, v143, v37
	v_fmac_f32_e32 v13, v143, v41
	v_fmac_f32_e32 v14, v143, v45
	v_fmac_f32_e32 v15, v143, v49
	v_fmac_f32_e32 v0, v143, v57
	ds_read_b128 v[50:53], v5 offset:48
	ds_read_b128 v[22:25], v5 offset:4144
	ds_read_b128 v[26:29], v5 offset:8240
	ds_read_b128 v[30:33], v5 offset:12336
	ds_read_b128 v[34:37], v5 offset:16432
	ds_read_b128 v[38:41], v5 offset:20528
	ds_read_b128 v[42:45], v5 offset:24624
	ds_read_b128 v[46:49], v5 offset:28720
	ds_read_b128 v[54:57], v5 offset:32816
	s_waitcnt vmcnt(16) lgkmcnt(0)
	v_fmac_f32_e32 v8, v146, v50
	v_fmac_f32_e32 v9, v146, v22
	v_fmac_f32_e32 v10, v146, v26
	v_fmac_f32_e32 v11, v146, v30
	v_fmac_f32_e32 v12, v146, v34
	v_fmac_f32_e32 v13, v146, v38
	v_fmac_f32_e32 v14, v146, v42
	v_fmac_f32_e32 v15, v146, v46
	v_fmac_f32_e32 v0, v146, v54
	v_fmac_f32_e32 v8, v147, v51
	v_fmac_f32_e32 v9, v147, v23
	v_fmac_f32_e32 v10, v147, v27
	v_fmac_f32_e32 v11, v147, v31
	v_fmac_f32_e32 v12, v147, v35
	v_fmac_f32_e32 v13, v147, v39
	v_fmac_f32_e32 v14, v147, v43
	v_fmac_f32_e32 v15, v147, v47
	v_fmac_f32_e32 v0, v147, v55
	v_fmac_f32_e32 v8, v148, v52
	v_fmac_f32_e32 v9, v148, v24
	v_fmac_f32_e32 v10, v148, v28
	v_fmac_f32_e32 v11, v148, v32
	v_fmac_f32_e32 v12, v148, v36
	v_fmac_f32_e32 v13, v148, v40
	v_fmac_f32_e32 v14, v148, v44
	v_fmac_f32_e32 v15, v148, v48
	v_fmac_f32_e32 v0, v148, v56
	v_fmac_f32_e32 v8, v149, v53
	v_fmac_f32_e32 v9, v149, v25
	v_fmac_f32_e32 v10, v149, v29
	v_fmac_f32_e32 v11, v149, v33
	v_fmac_f32_e32 v12, v149, v37
	v_fmac_f32_e32 v13, v149, v41
	v_fmac_f32_e32 v14, v149, v45
	v_fmac_f32_e32 v15, v149, v49
	v_fmac_f32_e32 v0, v149, v57
	s_add_i32 s12, s12, 64
	v_mov_b32_e32 v5, s12
	ds_read_b128 v[50:53], v5
	ds_read_b128 v[22:25], v5 offset:4096
	ds_read_b128 v[26:29], v5 offset:8192
	ds_read_b128 v[30:33], v5 offset:12288
	ds_read_b128 v[34:37], v5 offset:16384
	ds_read_b128 v[38:41], v5 offset:20480
	ds_read_b128 v[42:45], v5 offset:24576
	ds_read_b128 v[46:49], v5 offset:28672
	ds_read_b128 v[54:57], v5 offset:32768
	s_waitcnt vmcnt(12) lgkmcnt(0)
	v_fmac_f32_e32 v8, v150, v50
	v_fmac_f32_e32 v9, v150, v22
	v_fmac_f32_e32 v10, v150, v26
	v_fmac_f32_e32 v11, v150, v30
	v_fmac_f32_e32 v12, v150, v34
	v_fmac_f32_e32 v13, v150, v38
	v_fmac_f32_e32 v14, v150, v42
	v_fmac_f32_e32 v15, v150, v46
	v_fmac_f32_e32 v0, v150, v54
	v_fmac_f32_e32 v8, v151, v51
	v_fmac_f32_e32 v9, v151, v23
	v_fmac_f32_e32 v10, v151, v27
	v_fmac_f32_e32 v11, v151, v31
	v_fmac_f32_e32 v12, v151, v35
	v_fmac_f32_e32 v13, v151, v39
	v_fmac_f32_e32 v14, v151, v43
	v_fmac_f32_e32 v15, v151, v47
	v_fmac_f32_e32 v0, v151, v55
	v_fmac_f32_e32 v8, v152, v52
	v_fmac_f32_e32 v9, v152, v24
	v_fmac_f32_e32 v10, v152, v28
	v_fmac_f32_e32 v11, v152, v32
	v_fmac_f32_e32 v12, v152, v36
	v_fmac_f32_e32 v13, v152, v40
	v_fmac_f32_e32 v14, v152, v44
	v_fmac_f32_e32 v15, v152, v48
	v_fmac_f32_e32 v0, v152, v56
	v_fmac_f32_e32 v8, v153, v53
	v_fmac_f32_e32 v9, v153, v25
	v_fmac_f32_e32 v10, v153, v29
	v_fmac_f32_e32 v11, v153, v33
	v_fmac_f32_e32 v12, v153, v37
	v_fmac_f32_e32 v13, v153, v41
	v_fmac_f32_e32 v14, v153, v45
	v_fmac_f32_e32 v15, v153, v49
	v_fmac_f32_e32 v0, v153, v57
	ds_read_b128 v[50:53], v5 offset:16
	ds_read_b128 v[22:25], v5 offset:4112
	ds_read_b128 v[26:29], v5 offset:8208
	ds_read_b128 v[30:33], v5 offset:12304
	ds_read_b128 v[34:37], v5 offset:16400
	ds_read_b128 v[38:41], v5 offset:20496
	ds_read_b128 v[42:45], v5 offset:24592
	ds_read_b128 v[46:49], v5 offset:28688
	ds_read_b128 v[54:57], v5 offset:32784
	s_waitcnt vmcnt(8) lgkmcnt(0)
	v_fmac_f32_e32 v8, v154, v50
	v_fmac_f32_e32 v9, v154, v22
	v_fmac_f32_e32 v10, v154, v26
	v_fmac_f32_e32 v11, v154, v30
	v_fmac_f32_e32 v12, v154, v34
	v_fmac_f32_e32 v13, v154, v38
	v_fmac_f32_e32 v14, v154, v42
	v_fmac_f32_e32 v15, v154, v46
	v_fmac_f32_e32 v0, v154, v54
	v_fmac_f32_e32 v8, v155, v51
	v_fmac_f32_e32 v9, v155, v23
	v_fmac_f32_e32 v10, v155, v27
	v_fmac_f32_e32 v11, v155, v31
	v_fmac_f32_e32 v12, v155, v35
	v_fmac_f32_e32 v13, v155, v39
	v_fmac_f32_e32 v14, v155, v43
	v_fmac_f32_e32 v15, v155, v47
	v_fmac_f32_e32 v0, v155, v55
	v_fmac_f32_e32 v8, v156, v52
	v_fmac_f32_e32 v9, v156, v24
	v_fmac_f32_e32 v10, v156, v28
	v_fmac_f32_e32 v11, v156, v32
	v_fmac_f32_e32 v12, v156, v36
	v_fmac_f32_e32 v13, v156, v40
	v_fmac_f32_e32 v14, v156, v44
	v_fmac_f32_e32 v15, v156, v48
	v_fmac_f32_e32 v0, v156, v56
	v_fmac_f32_e32 v8, v157, v53
	v_fmac_f32_e32 v9, v157, v25
	v_fmac_f32_e32 v10, v157, v29
	v_fmac_f32_e32 v11, v157, v33
	v_fmac_f32_e32 v12, v157, v37
	v_fmac_f32_e32 v13, v157, v41
	v_fmac_f32_e32 v14, v157, v45
	v_fmac_f32_e32 v15, v157, v49
	v_fmac_f32_e32 v0, v157, v57
	ds_read_b128 v[50:53], v5 offset:32
	ds_read_b128 v[22:25], v5 offset:4128
	ds_read_b128 v[26:29], v5 offset:8224
	ds_read_b128 v[30:33], v5 offset:12320
	ds_read_b128 v[34:37], v5 offset:16416
	ds_read_b128 v[38:41], v5 offset:20512
	ds_read_b128 v[42:45], v5 offset:24608
	ds_read_b128 v[46:49], v5 offset:28704
	ds_read_b128 v[54:57], v5 offset:32800
	s_waitcnt vmcnt(4) lgkmcnt(0)
	v_fmac_f32_e32 v8, v158, v50
	v_fmac_f32_e32 v9, v158, v22
	v_fmac_f32_e32 v10, v158, v26
	v_fmac_f32_e32 v11, v158, v30
	v_fmac_f32_e32 v12, v158, v34
	v_fmac_f32_e32 v13, v158, v38
	v_fmac_f32_e32 v14, v158, v42
	v_fmac_f32_e32 v15, v158, v46
	v_fmac_f32_e32 v0, v158, v54
	v_fmac_f32_e32 v8, v159, v51
	v_fmac_f32_e32 v9, v159, v23
	v_fmac_f32_e32 v10, v159, v27
	v_fmac_f32_e32 v11, v159, v31
	v_fmac_f32_e32 v12, v159, v35
	v_fmac_f32_e32 v13, v159, v39
	v_fmac_f32_e32 v14, v159, v43
	v_fmac_f32_e32 v15, v159, v47
	v_fmac_f32_e32 v0, v159, v55
	v_fmac_f32_e32 v8, v160, v52
	v_fmac_f32_e32 v9, v160, v24
	v_fmac_f32_e32 v10, v160, v28
	v_fmac_f32_e32 v11, v160, v32
	v_fmac_f32_e32 v12, v160, v36
	v_fmac_f32_e32 v13, v160, v40
	v_fmac_f32_e32 v14, v160, v44
	v_fmac_f32_e32 v15, v160, v48
	v_fmac_f32_e32 v0, v160, v56
	v_fmac_f32_e32 v8, v161, v53
	v_fmac_f32_e32 v9, v161, v25
	v_fmac_f32_e32 v10, v161, v29
	v_fmac_f32_e32 v11, v161, v33
	v_fmac_f32_e32 v12, v161, v37
	v_fmac_f32_e32 v13, v161, v41
	v_fmac_f32_e32 v14, v161, v45
	v_fmac_f32_e32 v15, v161, v49
	v_fmac_f32_e32 v0, v161, v57
	ds_read_b128 v[50:53], v5 offset:48
	ds_read_b128 v[22:25], v5 offset:4144
	ds_read_b128 v[26:29], v5 offset:8240
	ds_read_b128 v[30:33], v5 offset:12336
	ds_read_b128 v[34:37], v5 offset:16432
	ds_read_b128 v[38:41], v5 offset:20528
	ds_read_b128 v[42:45], v5 offset:24624
	ds_read_b128 v[46:49], v5 offset:28720
	ds_read_b128 v[54:57], v5 offset:32816
	s_waitcnt vmcnt(0) lgkmcnt(0)
	v_fmac_f32_e32 v8, v162, v50
	v_fmac_f32_e32 v9, v162, v22
	v_fmac_f32_e32 v10, v162, v26
	v_fmac_f32_e32 v11, v162, v30
	v_fmac_f32_e32 v12, v162, v34
	v_fmac_f32_e32 v13, v162, v38
	v_fmac_f32_e32 v14, v162, v42
	v_fmac_f32_e32 v15, v162, v46
	v_fmac_f32_e32 v0, v162, v54
	v_fmac_f32_e32 v8, v163, v51
	v_fmac_f32_e32 v9, v163, v23
	v_fmac_f32_e32 v10, v163, v27
	v_fmac_f32_e32 v11, v163, v31
	v_fmac_f32_e32 v12, v163, v35
	v_fmac_f32_e32 v13, v163, v39
	v_fmac_f32_e32 v14, v163, v43
	v_fmac_f32_e32 v15, v163, v47
	v_fmac_f32_e32 v0, v163, v55
	v_fmac_f32_e32 v8, v164, v52
	v_fmac_f32_e32 v9, v164, v24
	v_fmac_f32_e32 v10, v164, v28
	v_fmac_f32_e32 v11, v164, v32
	v_fmac_f32_e32 v12, v164, v36
	v_fmac_f32_e32 v13, v164, v40
	v_fmac_f32_e32 v14, v164, v44
	v_fmac_f32_e32 v15, v164, v48
	v_fmac_f32_e32 v0, v164, v56
	v_fmac_f32_e32 v8, v165, v53
	v_fmac_f32_e32 v9, v165, v25
	v_fmac_f32_e32 v10, v165, v29
	v_fmac_f32_e32 v11, v165, v33
	v_fmac_f32_e32 v12, v165, v37
	v_fmac_f32_e32 v13, v165, v41
	v_fmac_f32_e32 v14, v165, v45
	v_fmac_f32_e32 v15, v165, v49
	v_fmac_f32_e32 v0, v165, v57
	ds_write2st64_b32 v20, v8, v9 offset0:144 offset1:145
	ds_write2st64_b32 v20, v10, v11 offset0:146 offset1:147
	ds_write2st64_b32 v20, v12, v13 offset0:148 offset1:149
	ds_write2st64_b32 v20, v14, v15 offset0:150 offset1:151
	ds_write_b32 v20, v0 offset:38912
	s_waitcnt lgkmcnt(0)
	s_barrier
	s_and_saveexec_b64 s[10:11], s[2:3]
	s_cbranch_execz .LBB0_20
	v_lshl_or_b32 v6, s21, 6, v144
	v_ashrrev_i32_e32 v7, 31, v6
	v_lshl_add_u64 v[6:7], v[6:7], 2, s[74:75]
	s_mov_b64 s[12:13], 0
	v_mov_b32_e32 v0, v19
	v_mov_b32_e32 v8, v18
	v_mov_b32_e32 v5, v17
